# v016 with all six GEMM K-loop heads aligned to 64 bytes (s_nop padding)
# baseline (speedup 1.0000x reference)
; template <class Epi, class Sched, bool APERM = false, bool HALFN = false>
; __device__ __forceinline__ void gemm_phase(LAS unsigned char* lds, const int tid_in, const int K, const Sched& S, const Epi& E) {
;     ...
;     for (;;) {
;         const bool has_next = S.next(ui + 1, nxt);
;         const char* nA = has_next ? nxt.A : cA; const char* nB = has_next ? nxt.B : cB;
;         for (int t = 0; t < nt; t += 2) {
.Lpfb_done:
	.p2alignl 6, 3212836864

; template <class Epi, class Sched, bool APERM = false, bool HALFN = false>
; __device__ __forceinline__ void gemm_phase(LAS unsigned char* lds, const int tid_in, const int K, const Sched& S, const Epi& E) {
;     ...
;         for (int t = 0; t < nt; t += 2) {
;     ...
; #pragma unroll
;         for (int a = 0; a < 2; ++a)
; #pragma unroll
;             for (int b = 0; b < 2; ++b)
; #pragma unroll
;                 for (int m = 0; m < 4; ++m)
; #pragma unroll
;                     for (int n = 0; n < 2; ++n) acc[a][b][m][n] = (f32x4){0.f, 0.f, 0.f, 0.f};
;         cur = nxt; cA = nA; cB = nB; ++ui;
.LBB0_681:
	s_add_u32 s45, s18, 0x100
	s_addc_u32 s52, s19, 0
	s_add_u32 s16, s16, 0x80080
	v_mov_b32_e32 v0, 0
	s_addc_u32 s17, s17, 0
	s_mov_b32 s53, -2
	s_waitcnt lgkmcnt(0)
	v_mov_b32_e32 v1, v0
	v_mov_b32_e32 v2, v0
	v_mov_b32_e32 v3, v0
	v_mov_b32_e32 v4, v0
	v_mov_b32_e32 v5, v0
	v_mov_b32_e32 v6, v0
	v_mov_b32_e32 v7, v0
	v_mov_b32_e32 v16, v0
	v_mov_b32_e32 v17, v0
	v_mov_b32_e32 v18, v0
	v_mov_b32_e32 v19, v0
	v_mov_b32_e32 v20, v0
	v_mov_b32_e32 v21, v0
	v_mov_b32_e32 v22, v0
	v_mov_b32_e32 v23, v0
	v_mov_b32_e32 v32, v0
	v_mov_b32_e32 v33, v0
	v_mov_b32_e32 v34, v0
	v_mov_b32_e32 v35, v0
	v_mov_b32_e32 v36, v0
	v_mov_b32_e32 v37, v0
	v_mov_b32_e32 v38, v0
	v_mov_b32_e32 v39, v0
	v_mov_b32_e32 v48, v0
	v_mov_b32_e32 v49, v0
	v_mov_b32_e32 v50, v0
	v_mov_b32_e32 v51, v0
	v_mov_b32_e32 v52, v0
	v_mov_b32_e32 v53, v0
	v_mov_b32_e32 v54, v0
	v_mov_b32_e32 v55, v0
	v_mov_b32_e32 v8, v0
	v_mov_b32_e32 v9, v0
	v_mov_b32_e32 v10, v0
	v_mov_b32_e32 v11, v0
	v_mov_b32_e32 v12, v0
	v_mov_b32_e32 v13, v0
	v_mov_b32_e32 v14, v0
	v_mov_b32_e32 v15, v0
	v_mov_b32_e32 v24, v0
	v_mov_b32_e32 v25, v0
	v_mov_b32_e32 v26, v0
	v_mov_b32_e32 v27, v0
	v_mov_b32_e32 v28, v0
	v_mov_b32_e32 v29, v0
	v_mov_b32_e32 v30, v0
	v_mov_b32_e32 v31, v0
	v_mov_b32_e32 v40, v0
	v_mov_b32_e32 v41, v0
	v_mov_b32_e32 v42, v0
	v_mov_b32_e32 v43, v0
	v_mov_b32_e32 v44, v0
	v_mov_b32_e32 v45, v0
	v_mov_b32_e32 v46, v0
	v_mov_b32_e32 v47, v0
	v_mov_b32_e32 v56, v0
	v_mov_b32_e32 v57, v0
	v_mov_b32_e32 v58, v0
	v_mov_b32_e32 v59, v0
	v_mov_b32_e32 v60, v0
	v_mov_b32_e32 v61, v0
	v_mov_b32_e32 v62, v0
	v_mov_b32_e32 v63, v0
	v_mov_b32_e32 v64, v0
	v_mov_b32_e32 v65, v0
	v_mov_b32_e32 v66, v0
	v_mov_b32_e32 v67, v0
	v_mov_b32_e32 v68, v0
	v_mov_b32_e32 v69, v0
	v_mov_b32_e32 v70, v0
	v_mov_b32_e32 v71, v0
	v_mov_b32_e32 v80, v0
	v_mov_b32_e32 v81, v0
	v_mov_b32_e32 v82, v0
	v_mov_b32_e32 v83, v0
	v_mov_b32_e32 v84, v0
	v_mov_b32_e32 v85, v0
	v_mov_b32_e32 v86, v0
	v_mov_b32_e32 v87, v0
	v_mov_b32_e32 v96, v0
	v_mov_b32_e32 v97, v0
	v_mov_b32_e32 v98, v0
	v_mov_b32_e32 v99, v0
	v_mov_b32_e32 v100, v0
	v_mov_b32_e32 v101, v0
	v_mov_b32_e32 v102, v0
	v_mov_b32_e32 v103, v0
	v_mov_b32_e32 v124, v0
	v_mov_b32_e32 v125, v0
	v_mov_b32_e32 v126, v0
	v_mov_b32_e32 v127, v0
	s_nop 0
	v_mov_b32_e32 v132, v0
	v_mov_b32_e32 v133, v0
	v_mov_b32_e32 v134, v0
	v_mov_b32_e32 v135, v0
	v_mov_b32_e32 v72, v0
	v_mov_b32_e32 v73, v0
	v_mov_b32_e32 v74, v0
	v_mov_b32_e32 v75, v0
	v_mov_b32_e32 v76, v0
	v_mov_b32_e32 v77, v0
	v_mov_b32_e32 v78, v0
	v_mov_b32_e32 v79, v0
	v_mov_b32_e32 v88, v0
	v_mov_b32_e32 v89, v0
	v_mov_b32_e32 v90, v0
	v_mov_b32_e32 v91, v0
	v_mov_b32_e32 v92, v0
	v_mov_b32_e32 v93, v0
	v_mov_b32_e32 v94, v0
	v_mov_b32_e32 v95, v0
	v_mov_b32_e32 v104, v0
	v_mov_b32_e32 v105, v0
	v_mov_b32_e32 v106, v0
	v_mov_b32_e32 v107, v0
	v_mov_b32_e32 v108, v0
	v_mov_b32_e32 v109, v0
	v_mov_b32_e32 v110, v0
	v_mov_b32_e32 v111, v0
	v_mov_b32_e32 v148, v0
	v_mov_b32_e32 v149, v0
	v_mov_b32_e32 v150, v0
	v_mov_b32_e32 v151, v0
	v_mov_b32_e32 v152, v0
	v_mov_b32_e32 v153, v0
	v_mov_b32_e32 v154, v0
	v_mov_b32_e32 v155, v0
	.p2alignl 6, 3212836864

; template <class Epi, class Sched, bool APERM = false, bool HALFN = false>
; __device__ __forceinline__ void gemm_phase(LAS unsigned char* lds, const int tid_in, const int K, const Sched& S, const Epi& E) {
;     ...
;         const bool has_next = S.next(ui + 1, nxt);
;         const char* nA = has_next ? nxt.A : cA; const char* nB = has_next ? nxt.B : cB;
;     ...
; #pragma unroll
;                 for (int m = 0; m < 4; ++m)
; #pragma unroll
;                     for (int n = 0; n < 2; ++n) acc[a][b][m][n] = (f32x4){0.f, 0.f, 0.f, 0.f};
;         cur = nxt; cA = nA; cB = nB; ++ui;
;     __device__ __forceinline__ bool next(int i, AB& u) const {
;         const int Lx = i * G + c; if (Lx >= 128) return false;
;         u.A = (const char*)(ws + WS_HB) + (size_t)(Lx & 31) * 256 * D_ * 2; u.B = (const char*)(ws + WS_W + (size_t)l * SZ_LAYER + OF_WQ) + (size_t)(Lx >> 5) * 128 * D_ * 2; return true;
.LBB0_765:
	s_mov_b32 s72, s71
	s_add_i32 s71, s71, 1
	s_mov_b64 s[18:19], s[6:7]
	s_mul_i32 s6, s71, s26
	s_mov_b64 s[20:21], s[8:9]
	s_add_i32 s8, s6, s24
	s_cmpk_lt_i32 s8, 0x80
	s_cselect_b64 s[16:17], -1, 0
	s_lshl_b32 s6, s8, 20
	s_and_b32 s6, s6, 0x1f00000
	s_add_u32 s6, s28, s6
	s_addc_u32 s7, s29, 0
	s_ashr_i32 s8, s8, 5
	s_ashr_i32 s9, s8, 31
	s_lshl_b64 s[8:9], s[8:9], 19
	s_add_u32 s8, s30, s8
	s_addc_u32 s9, s31, s9
	s_and_b64 s[22:23], s[16:17], exec
	s_cselect_b32 s74, s9, s21
	s_cselect_b32 s75, s8, s20
	s_cselect_b32 s76, s7, s19
	s_cselect_b32 s77, s6, s18
	s_add_u32 s80, s20, 0x100
	s_addc_u32 s81, s21, 0
	s_add_u32 s18, s18, 0x80080
	v_mov_b32_e32 v0, 0
	s_addc_u32 s19, s19, 0
	s_mov_b32 s86, -2
	v_mov_b32_e32 v1, v0
	v_mov_b32_e32 v2, v0
	v_mov_b32_e32 v3, v0
	v_mov_b32_e32 v4, v0
	v_mov_b32_e32 v5, v0
	v_mov_b32_e32 v6, v0
	v_mov_b32_e32 v7, v0
	v_mov_b32_e32 v8, v0
	v_mov_b32_e32 v9, v0
	v_mov_b32_e32 v10, v0
	v_mov_b32_e32 v11, v0
	v_mov_b32_e32 v12, v0
	v_mov_b32_e32 v13, v0
	v_mov_b32_e32 v14, v0
	v_mov_b32_e32 v15, v0
	v_mov_b32_e32 v16, v0
	v_mov_b32_e32 v17, v0
	v_mov_b32_e32 v18, v0
	v_mov_b32_e32 v19, v0
	v_mov_b32_e32 v20, v0
	v_mov_b32_e32 v21, v0
	v_mov_b32_e32 v22, v0
	v_mov_b32_e32 v23, v0
	v_mov_b32_e32 v24, v0
	v_mov_b32_e32 v25, v0
	v_mov_b32_e32 v26, v0
	v_mov_b32_e32 v27, v0
	v_mov_b32_e32 v28, v0
	v_mov_b32_e32 v29, v0
	v_mov_b32_e32 v30, v0
	v_mov_b32_e32 v31, v0
	v_mov_b32_e32 v32, v0
	v_mov_b32_e32 v33, v0
	v_mov_b32_e32 v34, v0
	v_mov_b32_e32 v35, v0
	v_mov_b32_e32 v36, v0
	v_mov_b32_e32 v37, v0
	v_mov_b32_e32 v38, v0
	v_mov_b32_e32 v39, v0
	v_mov_b32_e32 v40, v0
	v_mov_b32_e32 v41, v0
	v_mov_b32_e32 v42, v0
	v_mov_b32_e32 v43, v0
	v_mov_b32_e32 v44, v0
	v_mov_b32_e32 v45, v0
	v_mov_b32_e32 v46, v0
	v_mov_b32_e32 v47, v0
	v_mov_b32_e32 v48, v0
	v_mov_b32_e32 v49, v0
	v_mov_b32_e32 v50, v0
	v_mov_b32_e32 v51, v0
	v_mov_b32_e32 v52, v0
	v_mov_b32_e32 v53, v0
	v_mov_b32_e32 v54, v0
	v_mov_b32_e32 v55, v0
	v_mov_b32_e32 v56, v0
	v_mov_b32_e32 v57, v0
	v_mov_b32_e32 v58, v0
	v_mov_b32_e32 v59, v0
	v_mov_b32_e32 v60, v0
	v_mov_b32_e32 v61, v0
	v_mov_b32_e32 v62, v0
	v_mov_b32_e32 v63, v0
	s_nop 0
	.p2alignl 6, 3212836864

; template <class Epi, class Sched, bool APERM = false, bool HALFN = false>
; __device__ __forceinline__ void gemm_phase(LAS unsigned char* lds, const int tid_in, const int K, const Sched& S, const Epi& E) {
;     ...
;         for (int t = 0; t < nt; t += 2) {
;     ...
; #pragma unroll
;         for (int a = 0; a < 2; ++a)
; #pragma unroll
;             for (int b = 0; b < 2; ++b)
; #pragma unroll
;                 for (int m = 0; m < 4; ++m)
; #pragma unroll
;                     for (int n = 0; n < 2; ++n) acc[a][b][m][n] = (f32x4){0.f, 0.f, 0.f, 0.f};
;         cur = nxt; cA = nA; cB = nB; ++ui;
.LBB0_805:
	s_add_u32 s45, s18, 0x100
	s_addc_u32 s52, s19, 0
	s_add_u32 s16, s16, 0x20080
	v_mov_b32_e32 v0, 0
	s_addc_u32 s17, s17, 0
	s_mov_b32 s53, -2
	s_waitcnt lgkmcnt(0)
	v_mov_b32_e32 v1, v0
	v_mov_b32_e32 v2, v0
	v_mov_b32_e32 v3, v0
	v_mov_b32_e32 v4, v0
	v_mov_b32_e32 v5, v0
	v_mov_b32_e32 v6, v0
	v_mov_b32_e32 v7, v0
	v_mov_b32_e32 v16, v0
	v_mov_b32_e32 v17, v0
	v_mov_b32_e32 v18, v0
	v_mov_b32_e32 v19, v0
	v_mov_b32_e32 v20, v0
	v_mov_b32_e32 v21, v0
	v_mov_b32_e32 v22, v0
	v_mov_b32_e32 v23, v0
	v_mov_b32_e32 v32, v0
	v_mov_b32_e32 v33, v0
	v_mov_b32_e32 v34, v0
	v_mov_b32_e32 v35, v0
	v_mov_b32_e32 v36, v0
	v_mov_b32_e32 v37, v0
	v_mov_b32_e32 v38, v0
	v_mov_b32_e32 v39, v0
	v_mov_b32_e32 v48, v0
	v_mov_b32_e32 v49, v0
	v_mov_b32_e32 v50, v0
	v_mov_b32_e32 v51, v0
	v_mov_b32_e32 v52, v0
	v_mov_b32_e32 v53, v0
	v_mov_b32_e32 v54, v0
	v_mov_b32_e32 v55, v0
	v_mov_b32_e32 v8, v0
	v_mov_b32_e32 v9, v0
	v_mov_b32_e32 v10, v0
	v_mov_b32_e32 v11, v0
	v_mov_b32_e32 v12, v0
	v_mov_b32_e32 v13, v0
	v_mov_b32_e32 v14, v0
	v_mov_b32_e32 v15, v0
	v_mov_b32_e32 v24, v0
	v_mov_b32_e32 v25, v0
	v_mov_b32_e32 v26, v0
	v_mov_b32_e32 v27, v0
	v_mov_b32_e32 v28, v0
	v_mov_b32_e32 v29, v0
	v_mov_b32_e32 v30, v0
	v_mov_b32_e32 v31, v0
	v_mov_b32_e32 v40, v0
	v_mov_b32_e32 v41, v0
	v_mov_b32_e32 v42, v0
	v_mov_b32_e32 v43, v0
	v_mov_b32_e32 v44, v0
	v_mov_b32_e32 v45, v0
	v_mov_b32_e32 v46, v0
	v_mov_b32_e32 v47, v0
	v_mov_b32_e32 v56, v0
	v_mov_b32_e32 v57, v0
	v_mov_b32_e32 v58, v0
	v_mov_b32_e32 v59, v0
	v_mov_b32_e32 v60, v0
	v_mov_b32_e32 v61, v0
	v_mov_b32_e32 v62, v0
	v_mov_b32_e32 v63, v0
	v_mov_b32_e32 v64, v0
	v_mov_b32_e32 v65, v0
	v_mov_b32_e32 v66, v0
	v_mov_b32_e32 v67, v0
	v_mov_b32_e32 v68, v0
	v_mov_b32_e32 v69, v0
	v_mov_b32_e32 v70, v0
	v_mov_b32_e32 v71, v0
	v_mov_b32_e32 v80, v0
	v_mov_b32_e32 v81, v0
	v_mov_b32_e32 v82, v0
	v_mov_b32_e32 v83, v0
	v_mov_b32_e32 v84, v0
	v_mov_b32_e32 v85, v0
	v_mov_b32_e32 v86, v0
	v_mov_b32_e32 v87, v0
	v_mov_b32_e32 v96, v0
	v_mov_b32_e32 v97, v0
	v_mov_b32_e32 v98, v0
	v_mov_b32_e32 v99, v0
	v_mov_b32_e32 v100, v0
	v_mov_b32_e32 v101, v0
	v_mov_b32_e32 v102, v0
	v_mov_b32_e32 v103, v0
	v_mov_b32_e32 v124, v0
	v_mov_b32_e32 v125, v0
	v_mov_b32_e32 v126, v0
	v_mov_b32_e32 v127, v0
	s_nop 0
	v_mov_b32_e32 v132, v0
	v_mov_b32_e32 v133, v0
	v_mov_b32_e32 v134, v0
	v_mov_b32_e32 v135, v0
	v_mov_b32_e32 v72, v0
	v_mov_b32_e32 v73, v0
	v_mov_b32_e32 v74, v0
	v_mov_b32_e32 v75, v0
	v_mov_b32_e32 v76, v0
	v_mov_b32_e32 v77, v0
	v_mov_b32_e32 v78, v0
	v_mov_b32_e32 v79, v0
	v_mov_b32_e32 v88, v0
	v_mov_b32_e32 v89, v0
	v_mov_b32_e32 v90, v0
	v_mov_b32_e32 v91, v0
	v_mov_b32_e32 v92, v0
	v_mov_b32_e32 v93, v0
	v_mov_b32_e32 v94, v0
	v_mov_b32_e32 v95, v0
	v_mov_b32_e32 v104, v0
	v_mov_b32_e32 v105, v0
	v_mov_b32_e32 v106, v0
	v_mov_b32_e32 v107, v0
	v_mov_b32_e32 v108, v0
	v_mov_b32_e32 v109, v0
	v_mov_b32_e32 v110, v0
	v_mov_b32_e32 v111, v0
	v_mov_b32_e32 v148, v0
	v_mov_b32_e32 v149, v0
	v_mov_b32_e32 v150, v0
	v_mov_b32_e32 v151, v0
	v_mov_b32_e32 v152, v0
	v_mov_b32_e32 v153, v0
	v_mov_b32_e32 v154, v0
	v_mov_b32_e32 v155, v0
	.p2alignl 6, 3212836864

; template <class Epi, class Sched, bool APERM = false, bool HALFN = false>
; __device__ __forceinline__ void gemm_phase(LAS unsigned char* lds, const int tid_in, const int K, const Sched& S, const Epi& E) {
;     ...
;         for (int t = 0; t < nt; t += 2) {
;     ...
; #pragma unroll
;         for (int a = 0; a < 2; ++a)
; #pragma unroll
;             for (int b = 0; b < 2; ++b)
; #pragma unroll
;                 for (int m = 0; m < 4; ++m)
; #pragma unroll
;                     for (int n = 0; n < 2; ++n) acc[a][b][m][n] = (f32x4){0.f, 0.f, 0.f, 0.f};
;         cur = nxt; cA = nA; cB = nB; ++ui;
.LBB0_1032:
	s_add_u32 s53, s18, 0x100
	v_mov_b32_e32 v0, 0
	s_addc_u32 s57, s19, 0
	s_mov_b32 s70, -2
	s_waitcnt lgkmcnt(0)
	v_mov_b32_e32 v1, v0
	v_mov_b32_e32 v2, v0
	v_mov_b32_e32 v3, v0
	v_mov_b32_e32 v4, v0
	v_mov_b32_e32 v5, v0
	v_mov_b32_e32 v6, v0
	v_mov_b32_e32 v7, v0
	v_mov_b32_e32 v16, v0
	v_mov_b32_e32 v17, v0
	v_mov_b32_e32 v18, v0
	v_mov_b32_e32 v19, v0
	v_mov_b32_e32 v20, v0
	v_mov_b32_e32 v21, v0
	v_mov_b32_e32 v22, v0
	v_mov_b32_e32 v23, v0
	v_mov_b32_e32 v32, v0
	v_mov_b32_e32 v33, v0
	v_mov_b32_e32 v34, v0
	v_mov_b32_e32 v35, v0
	v_mov_b32_e32 v36, v0
	v_mov_b32_e32 v37, v0
	v_mov_b32_e32 v38, v0
	v_mov_b32_e32 v39, v0
	v_mov_b32_e32 v48, v0
	v_mov_b32_e32 v49, v0
	v_mov_b32_e32 v50, v0
	v_mov_b32_e32 v51, v0
	v_mov_b32_e32 v52, v0
	v_mov_b32_e32 v53, v0
	v_mov_b32_e32 v54, v0
	v_mov_b32_e32 v55, v0
	v_mov_b32_e32 v8, v0
	v_mov_b32_e32 v9, v0
	v_mov_b32_e32 v10, v0
	v_mov_b32_e32 v11, v0
	v_mov_b32_e32 v12, v0
	v_mov_b32_e32 v13, v0
	v_mov_b32_e32 v14, v0
	v_mov_b32_e32 v15, v0
	v_mov_b32_e32 v24, v0
	v_mov_b32_e32 v25, v0
	v_mov_b32_e32 v26, v0
	v_mov_b32_e32 v27, v0
	v_mov_b32_e32 v28, v0
	v_mov_b32_e32 v29, v0
	v_mov_b32_e32 v30, v0
	v_mov_b32_e32 v31, v0
	v_mov_b32_e32 v40, v0
	v_mov_b32_e32 v41, v0
	v_mov_b32_e32 v42, v0
	v_mov_b32_e32 v43, v0
	v_mov_b32_e32 v44, v0
	v_mov_b32_e32 v45, v0
	v_mov_b32_e32 v46, v0
	v_mov_b32_e32 v47, v0
	v_mov_b32_e32 v56, v0
	v_mov_b32_e32 v57, v0
	v_mov_b32_e32 v58, v0
	v_mov_b32_e32 v59, v0
	v_mov_b32_e32 v60, v0
	v_mov_b32_e32 v61, v0
	v_mov_b32_e32 v62, v0
	v_mov_b32_e32 v63, v0
	v_mov_b32_e32 v64, v0
	v_mov_b32_e32 v65, v0
	v_mov_b32_e32 v66, v0
	v_mov_b32_e32 v67, v0
	v_mov_b32_e32 v68, v0
	v_mov_b32_e32 v69, v0
	v_mov_b32_e32 v70, v0
	v_mov_b32_e32 v71, v0
	s_nop 0
	v_mov_b32_e32 v80, v0
	v_mov_b32_e32 v81, v0
	v_mov_b32_e32 v82, v0
	v_mov_b32_e32 v83, v0
	v_mov_b32_e32 v84, v0
	v_mov_b32_e32 v85, v0
	v_mov_b32_e32 v86, v0
	v_mov_b32_e32 v87, v0
	v_mov_b32_e32 v96, v0
	v_mov_b32_e32 v97, v0
	v_mov_b32_e32 v98, v0
	v_mov_b32_e32 v99, v0
	v_mov_b32_e32 v100, v0
	v_mov_b32_e32 v101, v0
	v_mov_b32_e32 v102, v0
	v_mov_b32_e32 v103, v0
	v_mov_b32_e32 v124, v0
	v_mov_b32_e32 v125, v0
	v_mov_b32_e32 v126, v0
	v_mov_b32_e32 v127, v0
	v_mov_b32_e32 v132, v0
	v_mov_b32_e32 v133, v0
	v_mov_b32_e32 v134, v0
	v_mov_b32_e32 v135, v0
	v_mov_b32_e32 v72, v0
	v_mov_b32_e32 v73, v0
	v_mov_b32_e32 v74, v0
	v_mov_b32_e32 v75, v0
	v_mov_b32_e32 v76, v0
	v_mov_b32_e32 v77, v0
	v_mov_b32_e32 v78, v0
	v_mov_b32_e32 v79, v0
	v_mov_b32_e32 v88, v0
	v_mov_b32_e32 v89, v0
	v_mov_b32_e32 v90, v0
	v_mov_b32_e32 v91, v0
	v_mov_b32_e32 v92, v0
	v_mov_b32_e32 v93, v0
	v_mov_b32_e32 v94, v0
	v_mov_b32_e32 v95, v0
	v_mov_b32_e32 v104, v0
	v_mov_b32_e32 v105, v0
	v_mov_b32_e32 v106, v0
	v_mov_b32_e32 v107, v0
	v_mov_b32_e32 v108, v0
	v_mov_b32_e32 v109, v0
	v_mov_b32_e32 v110, v0
	v_mov_b32_e32 v111, v0
	v_mov_b32_e32 v148, v0
	v_mov_b32_e32 v149, v0
	v_mov_b32_e32 v150, v0
	v_mov_b32_e32 v151, v0
	v_mov_b32_e32 v152, v0
	v_mov_b32_e32 v153, v0
	v_mov_b32_e32 v154, v0
	v_mov_b32_e32 v155, v0
	.p2alignl 6, 3212836864
